# v49 + P0 row pass: 64-lane sums by DPP quad_perm/row mirror + permlane swaps instead of six ds_bpermute hops
# baseline (speedup 1.0000x reference)
.LBB0_1918:
	s_waitcnt vmcnt(11)
	v_pk_mul_f32 v[44:45], v[82:83], v[82:83]
	v_pk_mul_f32 v[46:47], v[80:81], v[80:81]
	global_load_dwordx4 v[56:59], v2, s[6:7]
	global_load_dwordx4 v[52:55], v2, s[6:7] offset:1024
	v_pk_mov_b32 v[48:49], v[46:47], v[44:45] op_sel:[1,0]
	v_mov_b32_e32 v47, v45
	v_pk_add_f32 v[44:45], v[48:49], v[46:47]
	s_waitcnt vmcnt(12)
	v_pk_mul_f32 v[46:47], v[74:75], v[74:75]
	v_pk_mul_f32 v[48:49], v[72:73], v[72:73]
	v_pk_add_f32 v[44:45], v[44:45], v[44:45] op_sel:[0,1] op_sel_hi:[1,0]
	v_pk_mov_b32 v[50:51], v[48:49], v[46:47] op_sel:[1,0]
	v_mov_b32_e32 v49, v47
	v_pk_add_f32 v[46:47], v[50:51], v[48:49]
	s_waitcnt vmcnt(6)
	v_mul_f32_e32 v48, v28, v28
	v_mul_f32_e32 v49, v29, v29
	v_pk_add_f32 v[46:47], v[46:47], v[46:47] op_sel:[0,1] op_sel_hi:[1,0]
	v_mov_b32_e32 v45, v48
	v_mov_b32_e32 v47, v49
	v_pk_add_f32 v[44:45], v[44:45], v[46:47]
	v_mul_f32_e32 v46, v41, v41
	v_mul_f32_e32 v48, v43, v43
	v_mul_f32_e32 v50, v30, v30
	v_mul_f32_e32 v51, v31, v31
	v_pk_fma_f32 v[46:47], v[40:41], v[40:41], v[46:47] op_sel_hi:[1,1,0]
	v_pk_fma_f32 v[48:49], v[42:43], v[42:43], v[48:49] op_sel_hi:[1,1,0]
	v_mov_b32_e32 v47, v50
	v_mov_b32_e32 v49, v51
	v_pk_add_f32 v[46:47], v[46:47], v[48:49]
	s_lshr_b32 s10, s20, 10
	v_pk_add_f32 v[44:45], v[44:45], v[46:47]
	s_add_i32 s10, s10, 1
	v_add_f32_e32 v44, v44, v45
	s_nop 1
	v_mov_b32_dpp v45, v44 quad_perm:[1,0,3,2] row_mask:0xf bank_mask:0xf
	s_and_b64 s[4:5], exec, s[4:5]
	s_cselect_b32 s4, 0, s10
	s_mul_hi_u32 s5, s4, 0x6000
	s_mulk_i32 s4, 0x6000
	s_waitcnt lgkmcnt(0)
	v_add_f32_e32 v44, v44, v45
	s_nop 1
	v_mov_b32_dpp v45, v44 quad_perm:[2,3,0,1] row_mask:0xf bank_mask:0xf
	s_add_u32 s10, s26, s4
	s_addc_u32 s11, s27, s5
	v_lshl_add_u64 v[64:65], s[10:11], 0, v[2:3]
	v_lshl_add_u64 v[102:103], v[64:65], 0, s[24:25]
	s_waitcnt lgkmcnt(0)
	v_add_f32_e32 v44, v44, v45
	s_nop 1
	v_mov_b32_dpp v45, v44 row_half_mirror row_mask:0xf bank_mask:0xf
	v_add_co_u32_e32 v104, vcc, s23, v64
	s_waitcnt vmcnt(3)
	v_pk_add_f32 v[86:87], v[86:87], 1.0 op_sel_hi:[1,0]
	v_addc_co_u32_e32 v105, vcc, 0, v65, vcc
	s_waitcnt lgkmcnt(0)
	v_add_f32_e32 v44, v44, v45
	s_nop 1
	v_mov_b32_dpp v45, v44 row_mirror row_mask:0xf bank_mask:0xf
	v_pk_add_f32 v[84:85], v[84:85], 1.0 op_sel_hi:[1,0]
	v_pk_add_f32 v[70:71], v[70:71], 1.0 op_sel_hi:[1,0]
	v_pk_add_f32 v[68:69], v[68:69], 1.0 op_sel_hi:[1,0]
	v_pk_add_f32 v[32:33], v[32:33], 1.0 op_sel_hi:[1,0]
	s_waitcnt lgkmcnt(0)
	v_add_f32_e32 v48, v44, v45
	v_mov_b32_e32 v49, v48
	s_nop 1
	v_permlane16_swap_b32_e32 v48, v49
	global_load_dwordx4 v[44:47], v2, s[6:7] offset:3072
	v_pk_add_f32 v[34:35], v[34:35], 1.0 op_sel_hi:[1,0]
	s_waitcnt vmcnt(3)
	v_pk_add_f32 v[24:25], v[24:25], 1.0 op_sel_hi:[1,0]
	v_pk_add_f32 v[26:27], v[26:27], 1.0 op_sel_hi:[1,0]
	s_waitcnt lgkmcnt(0)
	v_add_f32_e32 v66, v48, v49
	global_load_dwordx4 v[48:51], v2, s[6:7] offset:2048
	v_mov_b32_e32 v67, v66
	s_nop 1
	v_permlane32_swap_b32_e32 v66, v67
	s_waitcnt lgkmcnt(0)
	v_add_f32_e32 v66, v66, v67
	v_fmamk_f32 v66, v66, 0x3a800000, v196
	v_mul_f32_e32 v67, 0x4f800000, v66
	v_cmp_gt_f32_e64 s[4:5], s31, v66
	s_nop 1
	v_cndmask_b32_e64 v66, v66, v67, s[4:5]
	v_sqrt_f32_e32 v67, v66
	s_nop 0
	v_add_u32_e32 v64, -1, v67
	v_fma_f32 v97, -v64, v67, v66
	v_cmp_ge_f32_e64 s[6:7], 0, v97
	v_add_u32_e32 v97, 1, v67
	s_nop 0
	v_cndmask_b32_e64 v64, v67, v64, s[6:7]
	v_fma_f32 v67, -v97, v67, v66
	v_cmp_lt_f32_e64 s[6:7], 0, v67
	s_nop 1
	v_cndmask_b32_e64 v64, v64, v97, s[6:7]
	v_mul_f32_e32 v67, 0x37800000, v64
	v_cndmask_b32_e64 v64, v64, v67, s[4:5]
	v_cmp_class_f32_e64 s[4:5], v66, v203
	s_nop 1
	v_cndmask_b32_e64 v97, v64, v66, s[4:5]
	v_div_scale_f32 v106, s[4:5], v97, v97, 1.0
	v_rcp_f32_e32 v107, v106
	global_load_dwordx4 v[98:101], v2, s[10:11]
	global_load_dwordx4 v[64:67], v2, s[10:11] offset:1024
	s_lshl_b64 s[4:5], s[16:17], 11
	s_add_i32 s16, s8, s85
	v_fma_f32 v108, -v106, v107, 1.0
	v_fmac_f32_e32 v107, v108, v107
	v_div_scale_f32 v108, vcc, 1.0, v97, 1.0
	v_mul_f32_e32 v109, v108, v107
	v_fma_f32 v110, -v106, v109, v108
	v_fmac_f32_e32 v109, v110, v107
	v_fma_f32 v106, -v106, v109, v108
	v_div_fmas_f32 v106, v106, v107, v109
	v_div_fixup_f32 v106, v106, v97, 1.0
	v_pk_mul_f32 v[82:83], v[82:83], v[106:107] op_sel_hi:[1,0]
	v_pk_mul_f32 v[80:81], v[80:81], v[106:107] op_sel_hi:[1,0]
	v_pk_mul_f32 v[74:75], v[74:75], v[106:107] op_sel_hi:[1,0]
	v_pk_mul_f32 v[72:73], v[72:73], v[106:107] op_sel_hi:[1,0]
	v_pk_mul_f32 v[80:81], v[4:5], v[80:81]
	v_pk_mul_f32 v[82:83], v[6:7], v[82:83]
	v_pk_mul_f32 v[72:73], v[8:9], v[72:73]
	v_pk_mul_f32 v[74:75], v[10:11], v[74:75]
	v_pk_fma_f32 v[108:109], v[86:87], v[82:83], v[78:79]
	v_pk_fma_f32 v[110:111], v[84:85], v[80:81], v[76:77]
	global_load_dwordx4 v[76:79], v[102:103], off offset:1024
	global_load_dwordx4 v[80:83], v[102:103], off offset:2048
	v_pk_fma_f32 v[112:113], v[70:71], v[74:75], v[62:63]
	v_pk_fma_f32 v[114:115], v[68:69], v[72:73], v[60:61]
	global_load_dwordx4 v[60:63], v2, s[10:11] offset:2048
	global_load_dwordx4 v[68:71], v2, s[10:11] offset:3072
	global_load_dwordx4 v[72:75], v[104:105], off
	global_load_dwordx4 v[84:87], v[102:103], off offset:3072
	s_waitcnt vmcnt(11)
	v_pk_mul_f32 v[102:103], v[58:59], v[58:59]
	v_pk_mul_f32 v[104:105], v[56:57], v[56:57]
	v_pk_mul_f32 v[40:41], v[40:41], v[106:107] op_sel_hi:[1,0]
	v_pk_mov_b32 v[116:117], v[104:105], v[102:103] op_sel:[1,0]
	v_mov_b32_e32 v105, v103
	v_pk_add_f32 v[102:103], v[116:117], v[104:105]
	s_waitcnt vmcnt(10)
	v_pk_mul_f32 v[104:105], v[54:55], v[54:55]
	v_pk_mul_f32 v[116:117], v[52:53], v[52:53]
	v_pk_add_f32 v[102:103], v[102:103], v[102:103] op_sel:[0,1] op_sel_hi:[1,0]
	v_pk_mov_b32 v[118:119], v[116:117], v[104:105] op_sel:[1,0]
	v_mov_b32_e32 v117, v105
	v_pk_add_f32 v[104:105], v[118:119], v[116:117]
	s_waitcnt vmcnt(9)
	v_mul_f32_e32 v103, v44, v44
	v_pk_add_f32 v[104:105], v[104:105], v[104:105] op_sel:[0,1] op_sel_hi:[1,0]
	v_pk_mul_f32 v[40:41], v[12:13], v[40:41]
	v_mul_f32_e32 v105, v45, v45
	s_waitcnt vmcnt(8)
	v_mul_f32_e32 v2, v49, v49
	v_pk_add_f32 v[102:103], v[102:103], v[104:105]
	v_pk_fma_f32 v[104:105], v[48:49], v[48:49], v[2:3] op_sel_hi:[1,1,0]
	v_mul_f32_e32 v2, v51, v51
	v_pk_fma_f32 v[116:117], v[50:51], v[50:51], v[2:3] op_sel_hi:[1,1,0]
	v_mul_f32_e32 v105, v46, v46
	v_mul_f32_e32 v117, v47, v47
	v_pk_add_f32 v[104:105], v[104:105], v[116:117]
	v_pk_fma_f32 v[32:33], v[32:33], v[40:41], v[36:37]
	v_pk_add_f32 v[102:103], v[102:103], v[104:105]
	v_pk_mul_f32 v[42:43], v[42:43], v[106:107] op_sel_hi:[1,0]
	v_add_f32_e32 v2, v102, v103
	s_nop 1
	v_mov_b32_dpp v97, v2 quad_perm:[1,0,3,2] row_mask:0xf bank_mask:0xf
	v_pk_mul_f32 v[42:43], v[14:15], v[42:43]
	v_lshl_add_u64 v[104:105], v[90:91], 0, s[4:5]
	v_pk_fma_f32 v[34:35], v[34:35], v[42:43], v[38:39]
	v_cvt_pk_bf16_f32 v32, v32, v33
	s_waitcnt lgkmcnt(0)
	v_add_f32_e32 v2, v2, v97
	s_nop 1
	v_mov_b32_dpp v97, v2 quad_perm:[2,3,0,1] row_mask:0xf bank_mask:0xf
	v_cvt_pk_bf16_f32 v33, v34, v35
	global_store_dwordx2 v[104:105], v[32:33], off offset:1024
	v_pk_mul_f32 v[28:29], v[28:29], v[106:107] op_sel_hi:[1,0]
	v_pk_mul_f32 v[30:31], v[30:31], v[106:107] op_sel_hi:[1,0]
	s_waitcnt lgkmcnt(0)
	v_add_f32_e32 v2, v2, v97
	s_nop 1
	v_mov_b32_dpp v97, v2 row_half_mirror row_mask:0xf bank_mask:0xf
	v_pk_mul_f32 v[28:29], v[16:17], v[28:29]
	v_pk_mul_f32 v[30:31], v[18:19], v[30:31]
	v_pk_fma_f32 v[20:21], v[24:25], v[28:29], v[20:21]
	v_pk_fma_f32 v[22:23], v[26:27], v[30:31], v[22:23]
	s_waitcnt lgkmcnt(0)
	v_add_f32_e32 v2, v2, v97
	s_nop 1
	v_mov_b32_dpp v97, v2 row_mirror row_mask:0xf bank_mask:0xf
	v_cvt_pk_bf16_f32 v20, v20, v21
	v_cvt_pk_bf16_f32 v21, v22, v23
	global_store_dwordx2 v[104:105], v[20:21], off offset:1536
	v_cvt_pk_bf16_f32 v102, v110, v111
	s_waitcnt lgkmcnt(0)
	v_add_f32_e32 v2, v2, v97
	v_mov_b32_e32 v36, v2
	s_nop 1
	v_permlane16_swap_b32_e32 v2, v36
	v_cvt_pk_bf16_f32 v103, v108, v109
	global_store_dwordx2 v[104:105], v[102:103], off
	v_cvt_pk_bf16_f32 v102, v114, v115
	v_cvt_pk_bf16_f32 v103, v112, v113
	s_waitcnt lgkmcnt(0)
	v_add_f32_e32 v2, v2, v36
	v_mov_b32_e32 v32, v2
	s_nop 1
	v_permlane32_swap_b32_e32 v2, v32
	global_store_dwordx2 v[104:105], v[102:103], off offset:512
	s_waitcnt lgkmcnt(0)
	v_add_f32_e32 v2, v2, v32
	v_fmamk_f32 v2, v2, 0x3a800000, v196
	v_mul_f32_e32 v32, 0x4f800000, v2
	v_cmp_gt_f32_e32 vcc, s31, v2
	s_waitcnt vmcnt(5)
	v_pk_add_f32 v[28:29], v[72:73], 1.0 op_sel_hi:[1,0]
	v_cndmask_b32_e32 v2, v2, v32, vcc
	v_sqrt_f32_e32 v32, v2
	s_nop 0
	v_add_u32_e32 v24, -1, v32
	v_fma_f32 v25, -v24, v32, v2
	v_cmp_ge_f32_e64 s[4:5], 0, v25
	v_add_u32_e32 v25, 1, v32
	v_fma_f32 v26, -v25, v32, v2
	v_cndmask_b32_e64 v24, v32, v24, s[4:5]
	v_cmp_lt_f32_e64 s[4:5], 0, v26
	v_pk_add_f32 v[26:27], v[74:75], 1.0 op_sel_hi:[1,0]
	s_nop 0
	v_cndmask_b32_e64 v24, v24, v25, s[4:5]
	v_mul_f32_e32 v25, 0x37800000, v24
	v_cndmask_b32_e32 v24, v24, v25, vcc
	v_cmp_class_f32_e32 vcc, v2, v203
	s_nop 1
	v_cndmask_b32_e32 v2, v24, v2, vcc
	v_div_scale_f32 v24, s[4:5], v2, v2, 1.0
	v_rcp_f32_e32 v25, v24
	s_lshl_b64 s[4:5], s[8:9], 11
	s_cmpk_gt_i32 s16, 0x1fff
	v_fma_f32 v20, -v24, v25, 1.0
	v_fmac_f32_e32 v25, v20, v25
	v_div_scale_f32 v20, vcc, 1.0, v2, 1.0
	v_mul_f32_e32 v21, v20, v25
	v_fma_f32 v22, -v24, v21, v20
	v_fmac_f32_e32 v21, v22, v25
	v_fma_f32 v20, -v24, v21, v20
	v_div_fmas_f32 v20, v20, v25, v21
	v_div_fixup_f32 v2, v20, v2, 1.0
	v_pk_mul_f32 v[22:23], v[58:59], v[2:3] op_sel_hi:[1,0]
	v_pk_mul_f32 v[24:25], v[56:57], v[2:3] op_sel_hi:[1,0]
	v_pk_mul_f32 v[22:23], v[6:7], v[22:23]
	v_pk_mul_f32 v[24:25], v[4:5], v[24:25]
	v_pk_fma_f32 v[22:23], v[26:27], v[22:23], v[100:101]
	v_pk_fma_f32 v[24:25], v[28:29], v[24:25], v[98:99]
	v_lshl_add_u64 v[20:21], v[90:91], 0, s[4:5]
	v_cvt_pk_bf16_f32 v24, v24, v25
	v_cvt_pk_bf16_f32 v25, v22, v23
	global_store_dwordx2 v[20:21], v[24:25], off
	v_pk_mul_f32 v[22:23], v[54:55], v[2:3] op_sel_hi:[1,0]
	v_pk_mul_f32 v[24:25], v[52:53], v[2:3] op_sel_hi:[1,0]
	v_pk_mul_f32 v[22:23], v[10:11], v[22:23]
	v_pk_mul_f32 v[24:25], v[8:9], v[24:25]
	v_pk_add_f32 v[26:27], v[78:79], 1.0 op_sel_hi:[1,0]
	v_pk_add_f32 v[28:29], v[76:77], 1.0 op_sel_hi:[1,0]
	v_pk_fma_f32 v[22:23], v[26:27], v[22:23], v[66:67]
	v_pk_fma_f32 v[24:25], v[28:29], v[24:25], v[64:65]
	v_pk_add_f32 v[26:27], v[82:83], 1.0 op_sel_hi:[1,0]
	v_cvt_pk_bf16_f32 v24, v24, v25
	v_cvt_pk_bf16_f32 v25, v22, v23
	global_store_dwordx2 v[20:21], v[24:25], off offset:512
	v_pk_mul_f32 v[22:23], v[50:51], v[2:3] op_sel_hi:[1,0]
	v_pk_mul_f32 v[24:25], v[48:49], v[2:3] op_sel_hi:[1,0]
	v_pk_mul_f32 v[22:23], v[14:15], v[22:23]
	v_pk_mul_f32 v[24:25], v[12:13], v[24:25]
	v_pk_add_f32 v[28:29], v[80:81], 1.0 op_sel_hi:[1,0]
	v_pk_fma_f32 v[22:23], v[26:27], v[22:23], v[62:63]
	v_pk_fma_f32 v[24:25], v[28:29], v[24:25], v[60:61]
	s_waitcnt vmcnt(6)
	v_pk_add_f32 v[26:27], v[86:87], 1.0 op_sel_hi:[1,0]
	v_cvt_pk_bf16_f32 v24, v24, v25
	v_cvt_pk_bf16_f32 v25, v22, v23
	global_store_dwordx2 v[20:21], v[24:25], off offset:1024
	v_pk_mul_f32 v[22:23], v[46:47], v[2:3] op_sel_hi:[1,0]
	v_pk_mul_f32 v[24:25], v[44:45], v[2:3] op_sel_hi:[1,0]
	v_pk_mul_f32 v[22:23], v[18:19], v[22:23]
	v_pk_mul_f32 v[24:25], v[16:17], v[24:25]
	v_pk_add_f32 v[28:29], v[84:85], 1.0 op_sel_hi:[1,0]
	v_pk_fma_f32 v[22:23], v[26:27], v[22:23], v[70:71]
	v_pk_fma_f32 v[24:25], v[28:29], v[24:25], v[68:69]
	s_nop 0
	v_cvt_pk_bf16_f32 v24, v24, v25
	v_cvt_pk_bf16_f32 v25, v22, v23
	global_store_dwordx2 v[20:21], v[24:25], off offset:1536
	s_cbranch_scc1 .LBB0_1923
